# attn2 step loop: mask load issued before the K/V tile loads, counted vmcnt(4) after issuing the next K/V pair, per-use waits before the second-half LDS write; K/V prefetch distance doubled for half of
# speedup vs baseline: 1.0021x; 1.0011x over previous
;     ...
;         const u64* mrow = nullptr; u64 wcur = 0, wnext = 0, wnext2 = 0;
;         if (MODE == 2) { mrow = bitmask + (size_t)(b * SEQ + myq) * 128; wcur = mrow[0]; }
;         f32x16 o[DVB];
; #pragma unroll
;         for (int db = 0; db < DVB; ++db)
; #pragma unroll
;             for (int i = 0; i < 16; ++i) o[db][i] = 0.f;
;         float m = -1e30f, l = 0.f;
;     ...
;         auto stepf = [&](f32x16 (&s_cur)[2], const float mi_cur, f32x16 (&s_nxt)[2], float& mi_nxt, u32x4 (&rg_ld)[NJ], float& ck_ld, const u32x4 (&rg_st)[NJ], const float ck_st, int kk) {
;             const int kt = j0 + kk;
;             if (DEEP) { if (kk + 3 < ntl) gload(rg_ld, ck_ld, kt + 3); } else { if (kk + 2 < ntl) gload(rg_ld, ck_ld, kt + 2); }
;             if (MODE == 2 && kk + 2 < ntl) wnext2 = mrow[kt + 2];
;             if (kk + 1 < ntl && (kt + 1) * 64 <= qw0 + 31) qk(s_nxt, mi_nxt, (kk + 1) % 3);
.LBB0_3603:
	s_or_b64 exec, exec, s[4:5]
	s_cmp_lt_i32 s40, 1
	s_cbranch_scc1 .LBB0_3591
	v_mad_i64_i32 v[4:5], s[0:1], v1, s29, 0
	v_lshl_add_u64 v[4:5], v[166:167], 0, v[4:5]
	v_mov_b32_e32 v16, v3
	v_mov_b32_e32 v17, v3
	v_lshl_add_u64 v[184:185], v[166:167], 0, v[6:7]
	v_lshl_add_u64 v[186:187], s[22:23], 1, v[4:5]
	v_mov_b32_e32 v2, v3
	v_mov_b32_e32 v4, v3
	v_mov_b32_e32 v5, v3
	v_mov_b32_e32 v6, v3
	v_mov_b32_e32 v7, v3
	v_mov_b32_e32 v8, v3
	v_mov_b32_e32 v9, v3
	v_mov_b32_e32 v10, v3
	v_mov_b32_e32 v11, v3
	v_mov_b32_e32 v12, v3
	v_mov_b32_e32 v13, v3
	v_mov_b32_e32 v14, v3
	v_mov_b32_e32 v15, v3
	v_mov_b64_e32 v[96:97], v[16:17]
	v_mov_b64_e32 v[112:113], v[16:17]
	v_or_b32_e32 v175, 31, v208
	s_mov_b32 s41, 1
	s_mov_b32 s44, 0
	v_mov_b32_e32 v183, 0xf149f2ca
	v_mov_b64_e32 v[190:191], 0
	v_mov_b32_e32 v188, 0
	s_mov_b32 s45, 4
	s_mov_b32 s46, 3
	s_mov_b32 s47, 2
	s_mov_b32 s48, 0
	v_mov_b64_e32 v[94:95], v[14:15]
	v_mov_b64_e32 v[92:93], v[12:13]
	v_mov_b64_e32 v[90:91], v[10:11]
	v_mov_b64_e32 v[88:89], v[8:9]
	v_mov_b64_e32 v[86:87], v[6:7]
	v_mov_b64_e32 v[84:85], v[4:5]
	v_mov_b64_e32 v[82:83], v[2:3]
	v_mov_b64_e32 v[110:111], v[14:15]
	v_mov_b64_e32 v[108:109], v[12:13]
	v_mov_b64_e32 v[106:107], v[10:11]
	v_mov_b64_e32 v[104:105], v[8:9]
	v_mov_b64_e32 v[102:103], v[6:7]
	v_mov_b64_e32 v[100:101], v[4:5]
	v_mov_b64_e32 v[98:99], v[2:3]
	s_mov_b32 s49, 0
	v_mov_b32_e32 v173, 0
	v_mov_b32_e32 v245, v3
	v_mov_b32_e32 v246, v3
	v_mov_b32_e32 v247, v3
	s_waitcnt vmcnt(0)
.LBB0_3605:
	s_mul_hi_u32 s54, s41, 0xaaaaaaab
	s_lshr_b32 s54, s54, 1
	s_mul_i32 s54, s54, 0xd800
	v_subrev_u32_e32 v211, s54, v202
	v_add_u32_e32 v211, s48, v211
	ds_read_b128 v[212:215], v211
	ds_read_b128 v[216:219], v211 offset:32
	ds_read_b128 v[220:223], v211 offset:64
	ds_read_b128 v[224:227], v211 offset:96
	ds_read_b128 v[228:231], v211 offset:4608
	ds_read_b128 v[232:235], v211 offset:4640
	ds_read_b128 v[236:239], v211 offset:4672
	ds_read_b128 v[240:243], v211 offset:4704
	s_add_i32 s50, s45, -2
	s_cmp_lt_i32 s50, s40
	s_cselect_b64 s[24:25], -1, 0
	s_cmp_ge_i32 s50, s40
	s_cbranch_scc1 .Lvm_a2top
	v_lshl_add_u64 v[4:5], s[42:43], 0, v[180:181]
	v_add_co_u32_e32 v4, vcc, 0x1d200000, v4
	s_nop 1
	v_addc_co_u32_e32 v5, vcc, 0, v5, vcc
	global_load_dwordx2 v[190:191], v[4:5], off offset:16

;     ...
;         auto gload = [&](u32x4 (&rg)[NJ], float& ckr, int t) {
; #pragma unroll
;             for (int j = 0; j < NJ; ++j) rg[j] = *(const u32x4*)(src[j] + (size_t)t * step[j]);
;             if (MODE == 1 && tid < 64) ckr = ckp[t * 64 + tid];
;         };
;         auto lstore = [&](const u32x4 (&rg)[NJ], const float ckr, int stg) {
;             unsigned char* sb = lds + stg * STG;
; #pragma unroll
;             for (int j = 0; j < NJ; ++j) {
;                 if (j < NKJ) *(u32x4*)(sb + j * 9216 + lrow * 144 + lkc * 16) = rg[j];
;                 else { unsigned char* d = sb + VT_OFF + (lrow + 64 * (j - NKJ)) * 136 + lkc * 16; u32x2 a, c; a.x = rg[j].x; a.y = rg[j].y; c.x = rg[j].z; c.y = rg[j].w; *(u32x2*)d = a; *(u32x2*)(d + 8) = c; }
;             }
;             if (MODE == 1 && tid < 64) *(float*)(sb + CK_OFF + tid * 4) = ckr;
;         };
;     ...
;             if (DEEP) { if (kk + 3 < ntl) gload(rg_ld, ck_ld, kt + 3); } else { if (kk + 2 < ntl) gload(rg_ld, ck_ld, kt + 2); }
;             if (MODE == 2 && kk + 2 < ntl) wnext2 = mrow[kt + 2];
;             if (kk + 1 < ntl && (kt + 1) * 64 <= qw0 + 31) qk(s_nxt, mi_nxt, (kk + 1) % 3);
;             if (kt * 64 <= qw0 + 31) softmax_pv(s_cur, mi_cur, kt, kk % 3);
;             if (MODE == 2) { wcur = wnext; wnext = wnext2; }
;             if (kk + 2 < ntl) lstore(rg_st, ck_st, (kk + 2) % 3);
;             __syncthreads();
.LBB0_3618:
	s_or_b64 exec, exec, s[26:27]
	s_mul_hi_u32 s0, s47, 0xaaaaaaab
	s_lshr_b32 s0, s0, 1
	s_andn2_b64 vcc, exec, s[24:25]
	s_mul_i32 s0, s0, 0xd800
	s_cbranch_vccnz .LBB0_3620
	v_subrev_u32_e32 v1, s0, v203
	v_add_u32_e32 v4, s48, v200
	v_subrev_u32_e32 v2, s0, v197
	v_add_u32_e32 v1, v4, v1
	ds_write_b128 v1, v[134:137]
	v_add3_u32 v1, v4, v2, s35
	ds_write2_b64 v1, v[138:139], v[140:141] offset1:1
.LBB0_3620:
	s_cmp_ge_i32 s52, s40
	s_waitcnt lgkmcnt(0)
	s_barrier
	s_cbranch_scc1 .LBB0_3631
	v_subrev_u32_e32 v211, s0, v204
	v_add_u32_e32 v211, s48, v211
	ds_read_b128 v[212:215], v211
	ds_read_b128 v[216:219], v211 offset:32
	ds_read_b128 v[220:223], v211 offset:64
	ds_read_b128 v[224:227], v211 offset:96
	ds_read_b128 v[228:231], v211 offset:4608
	ds_read_b128 v[232:235], v211 offset:4640
	ds_read_b128 v[236:239], v211 offset:4672
	ds_read_b128 v[240:243], v211 offset:4704
	s_cmp_ge_i32 s45, s40
	s_cbranch_scc1 .LBB0_3623
	v_lshl_add_u64 v[4:5], s[42:43], 0, v[186:187]
	v_add_co_u32_e32 v4, vcc, 0x73c0000, v4
	v_lshl_add_u64 v[6:7], s[42:43], 0, v[184:185]
	s_nop 0
	v_addc_co_u32_e32 v5, vcc, 0, v5, vcc
	v_add_co_u32_e32 v6, vcc, 0x15200000, v6
	s_nop 1
	v_addc_co_u32_e32 v7, vcc, 0, v7, vcc
	global_load_dwordx4 v[134:137], v[4:5], off offset:2048
	global_load_dwordx4 v[138:141], v[6:7], off offset:512
	s_waitcnt vmcnt(4)
	s_branch .Lmy_a2_w3join

;     ...
;         auto lstore = [&](const u32x4 (&rg)[NJ], const float ckr, int stg) {
;             unsigned char* sb = lds + stg * STG;
; #pragma unroll
;             for (int j = 0; j < NJ; ++j) {
;                 if (j < NKJ) *(u32x4*)(sb + j * 9216 + lrow * 144 + lkc * 16) = rg[j];
;                 else { unsigned char* d = sb + VT_OFF + (lrow + 64 * (j - NKJ)) * 136 + lkc * 16; u32x2 a, c; a.x = rg[j].x; a.y = rg[j].y; c.x = rg[j].z; c.y = rg[j].w; *(u32x2*)d = a; *(u32x2*)(d + 8) = c; }
;             }
;     ...
;             if (kk + 2 < ntl) lstore(rg_st, ck_st, (kk + 2) % 3);
.LBB0_3636:
	s_or_b64 exec, exec, s[24:25]
	s_and_b64 vcc, exec, s[4:5]
	s_cbranch_vccnz .LBB0_3638
	s_mul_hi_u32 s0, s46, 0xaaaaaaab
	s_lshr_b32 s0, s0, 1
	s_mul_i32 s0, s0, 0xd800
	v_subrev_u32_e32 v1, s0, v201
	v_add_u32_e32 v4, s48, v200
	v_subrev_u32_e32 v2, s0, v197
	v_add_u32_e32 v1, v4, v1
	s_waitcnt vmcnt(2)
	ds_write_b128 v1, v[158:161]
	v_add3_u32 v1, v4, v2, s36
	s_waitcnt vmcnt(1)
	ds_write2_b64 v1, v[162:163], v[164:165] offset1:1
